# scan: per-chunk global loads issued two chunks ahead (chunk loop unrolled x2, alternating load register sets)
# speedup vs baseline: 1.0104x; 1.0075x over previous
.LBB0_1063:
	s_andn2_b64 vcc, exec, s[0:1]
	s_cbranch_vccnz .LBB0_1071
	v_readlane_b32 s0, v207, 5
	v_readlane_b32 s1, v207, 6
	s_and_b64 s[0:1], s[0:1], exec
	v_readlane_b32 s0, v208, 26
	s_cselect_b32 s0, s0, s97
	s_and_b32 s7, s0, 3
	s_lshr_b32 s6, s0, 2
	s_lshr_b32 s9, s0, 5
	s_lshl_b32 s2, s6, 5
	s_and_b32 s2, s2, 0xc0
	s_and_b32 s3, s6, 1
	v_readlane_b32 s4, v210, 50
	v_readlane_b32 s5, v210, 51
	v_readlane_b32 s52, v210, 32
	v_readlane_b32 s53, v210, 33
	v_readlane_b32 s8, v208, 60
	s_cmp_eq_u32 s3, 0
	s_cselect_b32 s46, s14, s16
	s_cselect_b32 s47, s15, s17
	s_cselect_b32 s48, s18, s20
	s_cselect_b32 s49, s19, s21
	s_cselect_b32 s50, s26, s4
	s_cselect_b32 s51, s27, s5
	s_cselect_b32 s34, 16, -16
	s_cselect_b32 s10, 1, -1
	s_cselect_b32 s54, 0, 0xff
	s_cselect_b32 s55, 0, 0xfff
	s_lshl_b32 s0, s9, 8
	s_add_i32 s0, s0, 0x4000
	s_add_i32 s54, s54, s0
	s_lshl_b32 s0, s9, 12
	s_add_i32 s55, s55, s0
	s_setprio 3
	v_lshrrev_b32_e32 v119, 4, v133
	v_and_b32_e32 v120, 15, v133
	v_and_b32_e32 v121, 12, v120
	v_and_b32_e32 v0, 1, v120
	v_lshl_or_b32 v121, v0, 1, v121
	v_bfe_u32 v0, v120, 1, 1
	v_or_b32_e32 v121, v121, v0
	v_mul_i32_i24_e32 v0, s10, v119
	v_add_u32_e32 v113, s54, v0
	v_add_u32_e32 v117, s55, v0
	v_mul_i32_i24_e32 v0, s10, v121
	v_add_u32_e32 v114, s54, v0
	v_add_u32_e32 v126, s55, v0
	v_and_b32_e32 v0, 8, v120
	v_cmp_ne_u32_e64 s[38:39], 0, v0
	v_and_b32_e32 v0, 4, v120
	v_cmp_ne_u32_e64 s[40:41], 0, v0
	v_and_b32_e32 v0, 1, v120
	v_cmp_ne_u32_e64 s[42:43], 0, v0
	v_and_b32_e32 v0, 2, v120
	v_cmp_ne_u32_e64 s[44:45], 0, v0
	v_lshlrev_b32_e32 v0, 4, v120
	s_lshl_b32 s0, s2, 2
	v_add_u32_e32 v115, s0, v0
	s_lshl_b32 s1, s7, 4
	v_add_u32_e32 v122, s1, v119
	v_lshl_add_u32 v116, v122, 2, s0
	v_mov_b32_e32 v110, v0
	v_lshlrev_b32_e32 v111, 2, v122
	v_lshl_add_u32 v112, v119, 8, v0
	s_lshl_b32 s8, s8, 10
	s_add_u32 s52, s52, s8
	s_addc_u32 s53, s53, 0
	global_load_dwordx4 v[6:9], v115, s[52:53]
	v_mov_b32_e32 v2, 0
	v_mov_b32_e32 v3, 0
	v_mov_b32_e32 v4, 0
	v_mov_b32_e32 v5, 0
	v_mov_b32_e32 v82, 0
	v_mov_b32_e32 v83, 0
	v_mov_b32_e32 v84, 0
	v_mov_b32_e32 v85, 0
	v_mov_b32_e32 v92, 0
	s_mov_b32 s33, 0
	v_mul_u32_u24_e32 v0, 0xf00, v113
	v_lshl_add_u32 v125, v113, 10, v115
	v_add_u32_e32 v0, v0, v115
	v_add_u32_e32 v113, s34, v113
	global_load_dwordx4 v[22:25], v125, s[46:47]
	global_load_dwordx4 v[26:29], v125, s[48:49]
	global_load_dwordx4 v[30:33], v125, s[22:23]
	global_load_dwordx4 v[14:17], v0, s[12:13] offset:1024
	global_load_dwordx4 v[10:13], v0, s[12:13]
	global_load_dwordx4 v[18:21], v0, s[12:13] offset:2048
	s_waitcnt vmcnt(0)
	v_pk_add_f32 v[122:123], v[26:27], -1.0 op_sel_hi:[1,0]
	v_pk_add_f32 v[124:125], v[28:29], -1.0 op_sel_hi:[1,0]
	v_pk_mul_f32 v[118:119], v[30:31], v[26:27]
	v_pk_fma_f32 v[122:123], v[6:7], v[122:123], 1.0 op_sel_hi:[1,1,0]
	v_pk_fma_f32 v[124:125], v[8:9], v[124:125], 1.0 op_sel_hi:[1,1,0]
	v_pk_mul_f32 v[120:121], v[32:33], v[28:29]
	v_pk_mul_f32 v[122:123], v[14:15], v[122:123]
	v_pk_mul_f32 v[124:125], v[16:17], v[124:125]
	ds_write_b128 v112, v[22:25] offset:0
	ds_write_b128 v112, v[30:33] offset:4096
	ds_write_b128 v112, v[10:13] offset:16384
	ds_write_b128 v112, v[18:21] offset:20480
	ds_write_b128 v112, v[118:121] offset:8192
	ds_write_b128 v112, v[122:125] offset:12288
	s_waitcnt lgkmcnt(0)
	v_xor_b32_e32 v112, 0x6000, v112
	v_mul_u32_u24_e32 v0, 0xf00, v113
	v_lshl_add_u32 v125, v113, 10, v115
	v_add_u32_e32 v0, v0, v115
	v_add_u32_e32 v113, s34, v113
	global_load_dwordx4 v[146:149], v125, s[46:47]
	global_load_dwordx4 v[150:153], v125, s[48:49]
	global_load_dwordx4 v[154:157], v125, s[22:23]
	global_load_dwordx4 v[138:141], v0, s[12:13] offset:1024
	global_load_dwordx4 v[134:137], v0, s[12:13]
	global_load_dwordx4 v[142:145], v0, s[12:13] offset:2048
	s_barrier
.Lscan_chunk:
	ds_read_b128 v[38:41], v110 offset:4096
	ds_read_b128 v[34:37], v110 offset:0
	ds_read_b128 v[46:49], v110 offset:12288
	ds_read_b32 v54, v111 offset:20480
	ds_read_b128 v[42:45], v110 offset:8192
	ds_read_b128 v[50:53], v110 offset:16384
	ds_read_b128 v[60:63], v110 offset:4352
	ds_read_b128 v[56:59], v110 offset:256
	ds_read_b128 v[68:71], v110 offset:12544
	ds_read_b32 v76, v111 offset:20736
	ds_read_b128 v[64:67], v110 offset:8448
	ds_read_b128 v[72:75], v110 offset:16640
	s_cmpk_ge_i32 s33, 0x10e
	s_cbranch_scc1 .Lscan_skipload_a
	v_mul_u32_u24_e32 v0, 0xf00, v113
	v_lshl_add_u32 v125, v113, 10, v115
	v_add_u32_e32 v0, v0, v115
	v_add_u32_e32 v113, s34, v113
	global_load_dwordx4 v[22:25], v125, s[46:47]
	global_load_dwordx4 v[26:29], v125, s[48:49]
	global_load_dwordx4 v[30:33], v125, s[22:23]
	global_load_dwordx4 v[14:17], v0, s[12:13] offset:1024
	global_load_dwordx4 v[10:13], v0, s[12:13]
	global_load_dwordx4 v[18:21], v0, s[12:13] offset:2048
	s_cmp_eq_u32 s33, 13
	s_cbranch_scc0 .Lscan_nogload_a
	v_mov_b32_e32 v113, v117
	s_branch .Lscan_nogload_a
.Lscan_skipload_a:
	s_waitcnt vmcnt(0)
.Lscan_nogload_a:
	s_cmp_eq_u32 s33, 0
	s_cbranch_scc1 .Lscan_nored_a
	v_cndmask_b32_e64 v118, v102, v94, s[38:39]
	v_cndmask_b32_e64 v119, v103, v95, s[38:39]
	v_cndmask_b32_e64 v120, v104, v96, s[38:39]
	v_cndmask_b32_e64 v121, v105, v97, s[38:39]
	v_cndmask_b32_e64 v122, v106, v98, s[38:39]
	v_cndmask_b32_e64 v123, v107, v99, s[38:39]
	v_cndmask_b32_e64 v124, v108, v100, s[38:39]
	v_cndmask_b32_e64 v125, v109, v101, s[38:39]
	v_cndmask_b32_e64 v94, v94, v102, s[38:39]
	v_cndmask_b32_e64 v95, v95, v103, s[38:39]
	v_cndmask_b32_e64 v96, v96, v104, s[38:39]
	v_cndmask_b32_e64 v97, v97, v105, s[38:39]
	v_cndmask_b32_e64 v98, v98, v106, s[38:39]
	v_cndmask_b32_e64 v99, v99, v107, s[38:39]
	v_cndmask_b32_e64 v100, v100, v108, s[38:39]
	v_cndmask_b32_e64 v101, v101, v109, s[38:39]
	v_add_f32_dpp v94, v118, v94 row_ror:8 row_mask:0xf bank_mask:0xf bound_ctrl:1
	v_add_f32_dpp v95, v119, v95 row_ror:8 row_mask:0xf bank_mask:0xf bound_ctrl:1
	v_add_f32_dpp v96, v120, v96 row_ror:8 row_mask:0xf bank_mask:0xf bound_ctrl:1
	v_add_f32_dpp v97, v121, v97 row_ror:8 row_mask:0xf bank_mask:0xf bound_ctrl:1
	v_add_f32_dpp v98, v122, v98 row_ror:8 row_mask:0xf bank_mask:0xf bound_ctrl:1
	v_add_f32_dpp v99, v123, v99 row_ror:8 row_mask:0xf bank_mask:0xf bound_ctrl:1
	v_add_f32_dpp v100, v124, v100 row_ror:8 row_mask:0xf bank_mask:0xf bound_ctrl:1
	v_add_f32_dpp v101, v125, v101 row_ror:8 row_mask:0xf bank_mask:0xf bound_ctrl:1
	v_cndmask_b32_e64 v118, v98, v94, s[40:41]
	v_cndmask_b32_e64 v119, v99, v95, s[40:41]
	v_cndmask_b32_e64 v120, v100, v96, s[40:41]
	v_cndmask_b32_e64 v121, v101, v97, s[40:41]
	v_cndmask_b32_e64 v94, v94, v98, s[40:41]
	v_cndmask_b32_e64 v95, v95, v99, s[40:41]
	v_cndmask_b32_e64 v96, v96, v100, s[40:41]
	v_cndmask_b32_e64 v97, v97, v101, s[40:41]
	v_add_f32_dpp v94, v118, v94 row_half_mirror row_mask:0xf bank_mask:0xf bound_ctrl:1
	v_add_f32_dpp v95, v119, v95 row_half_mirror row_mask:0xf bank_mask:0xf bound_ctrl:1
	v_add_f32_dpp v96, v120, v96 row_half_mirror row_mask:0xf bank_mask:0xf bound_ctrl:1
	v_add_f32_dpp v97, v121, v97 row_half_mirror row_mask:0xf bank_mask:0xf bound_ctrl:1
	v_cndmask_b32_e64 v118, v96, v94, s[42:43]
	v_cndmask_b32_e64 v119, v97, v95, s[42:43]
	v_cndmask_b32_e64 v94, v94, v96, s[42:43]
	v_cndmask_b32_e64 v95, v95, v97, s[42:43]
	s_nop 0
	v_add_f32_dpp v94, v118, v94 quad_perm:[1,0,3,2] row_mask:0xf bank_mask:0xf bound_ctrl:1
	v_add_f32_dpp v95, v119, v95 quad_perm:[1,0,3,2] row_mask:0xf bank_mask:0xf bound_ctrl:1
	s_nop 0
	v_cndmask_b32_e64 v118, v95, v94, s[44:45]
	v_cndmask_b32_e64 v94, v94, v95, s[44:45]
	s_nop 1
	v_add_f32_dpp v94, v118, v94 quad_perm:[2,3,0,1] row_mask:0xf bank_mask:0xf bound_ctrl:1
	v_lshl_add_u32 v0, v114, 10, v116
	v_add_u32_e32 v114, s34, v114
	global_store_dword v0, v94, s[50:51]
	s_cmp_eq_u32 s33, 16
	s_cbranch_scc0 .Lscan_nored_a
	v_mov_b32_e32 v114, v126
.Lscan_nored_a:
	s_waitcnt lgkmcnt(1)
	v_pk_mul_f32 v[86:87], v[2:3], v[38:39]
	v_pk_mul_f32 v[78:79], v[2:3], v[34:35]
	v_pk_fma_f32 v[86:87], v[4:5], v[40:41], v[86:87]
	v_pk_mul_f32 v[80:81], v[4:5], v[36:37]
	ds_read_b128 v[38:41], v110 offset:4608
	v_add_f32_e32 v90, v86, v87
	v_pk_fma_f32 v[82:83], v[54:55], v[46:47], v[78:79] op_sel_hi:[0,1,1]
	ds_read_b128 v[34:37], v110 offset:512
	v_add_f32_dpp v90, v90, v90 quad_perm:[1,0,3,2] row_mask:0xf bank_mask:0xf bound_ctrl:1
	v_pk_fma_f32 v[84:85], v[54:55], v[48:49], v[80:81] op_sel_hi:[0,1,1]
	ds_read_b128 v[46:49], v110 offset:12800
	v_add_f32_dpp v90, v90, v90 quad_perm:[2,3,0,1] row_mask:0xf bank_mask:0xf bound_ctrl:1
	ds_read_b32 v54, v111 offset:20992
	s_nop 0
	v_add_f32_dpp v90, v90, v90 row_half_mirror row_mask:0xf bank_mask:0xf bound_ctrl:1
	s_nop 0
	s_nop 0
	v_add_f32_dpp v92, v90, v90 row_mirror row_mask:0xf bank_mask:0xf bound_ctrl:1
	v_pk_fma_f32 v[2:3], v[92:93], v[42:43], v[82:83] op_sel_hi:[0,1,1] neg_lo:[1,0,0] neg_hi:[1,0,0]
	v_pk_fma_f32 v[4:5], v[92:93], v[44:45], v[84:85] op_sel_hi:[0,1,1] neg_lo:[1,0,0] neg_hi:[1,0,0]
	ds_read_b128 v[42:45], v110 offset:8704
	v_pk_mul_f32 v[86:87], v[2:3], v[60:61]
	v_pk_mul_f32 v[78:79], v[2:3], v[56:57]
	v_pk_fma_f32 v[86:87], v[4:5], v[62:63], v[86:87]
	v_pk_mul_f32 v[80:81], v[4:5], v[58:59]
	v_pk_mul_f32 v[88:89], v[2:3], v[50:51]
	v_add_f32_e32 v90, v86, v87
	v_pk_fma_f32 v[82:83], v[76:77], v[68:69], v[78:79] op_sel_hi:[0,1,1]
	v_pk_fma_f32 v[88:89], v[4:5], v[52:53], v[88:89]
	v_add_f32_dpp v90, v90, v90 quad_perm:[1,0,3,2] row_mask:0xf bank_mask:0xf bound_ctrl:1
	v_pk_fma_f32 v[84:85], v[76:77], v[70:71], v[80:81] op_sel_hi:[0,1,1]
	ds_read_b128 v[60:63], v110 offset:4864
	v_add_f32_dpp v90, v90, v90 quad_perm:[2,3,0,1] row_mask:0xf bank_mask:0xf bound_ctrl:1
	ds_read_b128 v[56:59], v110 offset:768
	v_add_f32_e32 v94, v88, v89
	v_add_f32_dpp v90, v90, v90 row_half_mirror row_mask:0xf bank_mask:0xf bound_ctrl:1
	ds_read_b128 v[50:53], v110 offset:16896
	ds_read_b128 v[68:71], v110 offset:13056
	v_add_f32_dpp v92, v90, v90 row_mirror row_mask:0xf bank_mask:0xf bound_ctrl:1
	ds_read_b32 v76, v111 offset:21248
	v_pk_fma_f32 v[2:3], v[92:93], v[64:65], v[82:83] op_sel_hi:[0,1,1] neg_lo:[1,0,0] neg_hi:[1,0,0]
	v_pk_fma_f32 v[4:5], v[92:93], v[66:67], v[84:85] op_sel_hi:[0,1,1] neg_lo:[1,0,0] neg_hi:[1,0,0]
	ds_read_b128 v[64:67], v110 offset:8960
	s_waitcnt lgkmcnt(6)
	v_pk_mul_f32 v[86:87], v[2:3], v[38:39]
	v_pk_mul_f32 v[78:79], v[2:3], v[34:35]
	v_pk_fma_f32 v[86:87], v[4:5], v[40:41], v[86:87]
	v_pk_mul_f32 v[80:81], v[4:5], v[36:37]
	v_pk_mul_f32 v[88:89], v[2:3], v[72:73]
	v_add_f32_e32 v90, v86, v87
	v_pk_fma_f32 v[82:83], v[54:55], v[46:47], v[78:79] op_sel_hi:[0,1,1]
	v_pk_fma_f32 v[88:89], v[4:5], v[74:75], v[88:89]
	v_add_f32_dpp v90, v90, v90 quad_perm:[1,0,3,2] row_mask:0xf bank_mask:0xf bound_ctrl:1
	v_pk_fma_f32 v[84:85], v[54:55], v[48:49], v[80:81] op_sel_hi:[0,1,1]
	ds_read_b128 v[38:41], v110 offset:5120
	v_add_f32_dpp v90, v90, v90 quad_perm:[2,3,0,1] row_mask:0xf bank_mask:0xf bound_ctrl:1
	ds_read_b128 v[34:37], v110 offset:1024
	v_add_f32_e32 v95, v88, v89
	v_add_f32_dpp v90, v90, v90 row_half_mirror row_mask:0xf bank_mask:0xf bound_ctrl:1
	ds_read_b128 v[72:75], v110 offset:17152
	ds_read_b128 v[46:49], v110 offset:13312
	v_add_f32_dpp v92, v90, v90 row_mirror row_mask:0xf bank_mask:0xf bound_ctrl:1
	ds_read_b32 v54, v111 offset:21504
	v_pk_fma_f32 v[2:3], v[92:93], v[42:43], v[82:83] op_sel_hi:[0,1,1] neg_lo:[1,0,0] neg_hi:[1,0,0]
	v_pk_fma_f32 v[4:5], v[92:93], v[44:45], v[84:85] op_sel_hi:[0,1,1] neg_lo:[1,0,0] neg_hi:[1,0,0]
	ds_read_b128 v[42:45], v110 offset:9216
	s_waitcnt lgkmcnt(6)
	v_pk_mul_f32 v[86:87], v[2:3], v[60:61]
	v_pk_mul_f32 v[78:79], v[2:3], v[56:57]
	v_pk_fma_f32 v[86:87], v[4:5], v[62:63], v[86:87]
	v_pk_mul_f32 v[80:81], v[4:5], v[58:59]
	v_pk_mul_f32 v[88:89], v[2:3], v[50:51]
	v_add_f32_e32 v90, v86, v87
	v_pk_fma_f32 v[82:83], v[76:77], v[68:69], v[78:79] op_sel_hi:[0,1,1]
	v_pk_fma_f32 v[88:89], v[4:5], v[52:53], v[88:89]
	v_add_f32_dpp v90, v90, v90 quad_perm:[1,0,3,2] row_mask:0xf bank_mask:0xf bound_ctrl:1
	v_pk_fma_f32 v[84:85], v[76:77], v[70:71], v[80:81] op_sel_hi:[0,1,1]
	ds_read_b128 v[60:63], v110 offset:5376
	v_add_f32_dpp v90, v90, v90 quad_perm:[2,3,0,1] row_mask:0xf bank_mask:0xf bound_ctrl:1
	ds_read_b128 v[56:59], v110 offset:1280
	v_add_f32_e32 v96, v88, v89
	v_add_f32_dpp v90, v90, v90 row_half_mirror row_mask:0xf bank_mask:0xf bound_ctrl:1
	ds_read_b128 v[50:53], v110 offset:17408
	ds_read_b128 v[68:71], v110 offset:13568
	v_add_f32_dpp v92, v90, v90 row_mirror row_mask:0xf bank_mask:0xf bound_ctrl:1
	ds_read_b32 v76, v111 offset:21760
	v_pk_fma_f32 v[2:3], v[92:93], v[64:65], v[82:83] op_sel_hi:[0,1,1] neg_lo:[1,0,0] neg_hi:[1,0,0]
	v_pk_fma_f32 v[4:5], v[92:93], v[66:67], v[84:85] op_sel_hi:[0,1,1] neg_lo:[1,0,0] neg_hi:[1,0,0]
	ds_read_b128 v[64:67], v110 offset:9472
	s_waitcnt lgkmcnt(6)
	v_pk_mul_f32 v[86:87], v[2:3], v[38:39]
	v_pk_mul_f32 v[78:79], v[2:3], v[34:35]
	v_pk_fma_f32 v[86:87], v[4:5], v[40:41], v[86:87]
	v_pk_mul_f32 v[80:81], v[4:5], v[36:37]
	v_pk_mul_f32 v[88:89], v[2:3], v[72:73]
	v_add_f32_e32 v90, v86, v87
	v_pk_fma_f32 v[82:83], v[54:55], v[46:47], v[78:79] op_sel_hi:[0,1,1]
	v_pk_fma_f32 v[88:89], v[4:5], v[74:75], v[88:89]
	v_add_f32_dpp v90, v90, v90 quad_perm:[1,0,3,2] row_mask:0xf bank_mask:0xf bound_ctrl:1
	v_pk_fma_f32 v[84:85], v[54:55], v[48:49], v[80:81] op_sel_hi:[0,1,1]
	ds_read_b128 v[38:41], v110 offset:5632
	v_add_f32_dpp v90, v90, v90 quad_perm:[2,3,0,1] row_mask:0xf bank_mask:0xf bound_ctrl:1
	ds_read_b128 v[34:37], v110 offset:1536
	v_add_f32_e32 v97, v88, v89
	v_add_f32_dpp v90, v90, v90 row_half_mirror row_mask:0xf bank_mask:0xf bound_ctrl:1
	ds_read_b128 v[72:75], v110 offset:17664
	ds_read_b128 v[46:49], v110 offset:13824
	v_add_f32_dpp v92, v90, v90 row_mirror row_mask:0xf bank_mask:0xf bound_ctrl:1
	ds_read_b32 v54, v111 offset:22016
	v_pk_fma_f32 v[2:3], v[92:93], v[42:43], v[82:83] op_sel_hi:[0,1,1] neg_lo:[1,0,0] neg_hi:[1,0,0]
	v_pk_fma_f32 v[4:5], v[92:93], v[44:45], v[84:85] op_sel_hi:[0,1,1] neg_lo:[1,0,0] neg_hi:[1,0,0]
	ds_read_b128 v[42:45], v110 offset:9728
	s_waitcnt lgkmcnt(6)
	v_pk_mul_f32 v[86:87], v[2:3], v[60:61]
	v_pk_mul_f32 v[78:79], v[2:3], v[56:57]
	v_pk_fma_f32 v[86:87], v[4:5], v[62:63], v[86:87]
	v_pk_mul_f32 v[80:81], v[4:5], v[58:59]
	v_pk_mul_f32 v[88:89], v[2:3], v[50:51]
	v_add_f32_e32 v90, v86, v87
	v_pk_fma_f32 v[82:83], v[76:77], v[68:69], v[78:79] op_sel_hi:[0,1,1]
	v_pk_fma_f32 v[88:89], v[4:5], v[52:53], v[88:89]
	v_add_f32_dpp v90, v90, v90 quad_perm:[1,0,3,2] row_mask:0xf bank_mask:0xf bound_ctrl:1
	v_pk_fma_f32 v[84:85], v[76:77], v[70:71], v[80:81] op_sel_hi:[0,1,1]
	ds_read_b128 v[60:63], v110 offset:5888
	v_add_f32_dpp v90, v90, v90 quad_perm:[2,3,0,1] row_mask:0xf bank_mask:0xf bound_ctrl:1
	ds_read_b128 v[56:59], v110 offset:1792
	v_add_f32_e32 v98, v88, v89
	v_add_f32_dpp v90, v90, v90 row_half_mirror row_mask:0xf bank_mask:0xf bound_ctrl:1
	ds_read_b128 v[50:53], v110 offset:17920
	ds_read_b128 v[68:71], v110 offset:14080
	v_add_f32_dpp v92, v90, v90 row_mirror row_mask:0xf bank_mask:0xf bound_ctrl:1
	ds_read_b32 v76, v111 offset:22272
	v_pk_fma_f32 v[2:3], v[92:93], v[64:65], v[82:83] op_sel_hi:[0,1,1] neg_lo:[1,0,0] neg_hi:[1,0,0]
	v_pk_fma_f32 v[4:5], v[92:93], v[66:67], v[84:85] op_sel_hi:[0,1,1] neg_lo:[1,0,0] neg_hi:[1,0,0]
	ds_read_b128 v[64:67], v110 offset:9984
	s_waitcnt lgkmcnt(6)
	v_pk_mul_f32 v[86:87], v[2:3], v[38:39]
	v_pk_mul_f32 v[78:79], v[2:3], v[34:35]
	v_pk_fma_f32 v[86:87], v[4:5], v[40:41], v[86:87]
	v_pk_mul_f32 v[80:81], v[4:5], v[36:37]
	v_pk_mul_f32 v[88:89], v[2:3], v[72:73]
	v_add_f32_e32 v90, v86, v87
	v_pk_fma_f32 v[82:83], v[54:55], v[46:47], v[78:79] op_sel_hi:[0,1,1]
	v_pk_fma_f32 v[88:89], v[4:5], v[74:75], v[88:89]
	v_add_f32_dpp v90, v90, v90 quad_perm:[1,0,3,2] row_mask:0xf bank_mask:0xf bound_ctrl:1
	v_pk_fma_f32 v[84:85], v[54:55], v[48:49], v[80:81] op_sel_hi:[0,1,1]
	ds_read_b128 v[38:41], v110 offset:6144
	v_add_f32_dpp v90, v90, v90 quad_perm:[2,3,0,1] row_mask:0xf bank_mask:0xf bound_ctrl:1
	ds_read_b128 v[34:37], v110 offset:2048
	v_add_f32_e32 v99, v88, v89
	v_add_f32_dpp v90, v90, v90 row_half_mirror row_mask:0xf bank_mask:0xf bound_ctrl:1
	ds_read_b128 v[72:75], v110 offset:18176
	ds_read_b128 v[46:49], v110 offset:14336
	v_add_f32_dpp v92, v90, v90 row_mirror row_mask:0xf bank_mask:0xf bound_ctrl:1
	ds_read_b32 v54, v111 offset:22528
	v_pk_fma_f32 v[2:3], v[92:93], v[42:43], v[82:83] op_sel_hi:[0,1,1] neg_lo:[1,0,0] neg_hi:[1,0,0]
	v_pk_fma_f32 v[4:5], v[92:93], v[44:45], v[84:85] op_sel_hi:[0,1,1] neg_lo:[1,0,0] neg_hi:[1,0,0]
	ds_read_b128 v[42:45], v110 offset:10240
	s_waitcnt lgkmcnt(6)
	v_pk_mul_f32 v[86:87], v[2:3], v[60:61]
	v_pk_mul_f32 v[78:79], v[2:3], v[56:57]
	v_pk_fma_f32 v[86:87], v[4:5], v[62:63], v[86:87]
	v_pk_mul_f32 v[80:81], v[4:5], v[58:59]
	v_pk_mul_f32 v[88:89], v[2:3], v[50:51]
	v_add_f32_e32 v90, v86, v87
	v_pk_fma_f32 v[82:83], v[76:77], v[68:69], v[78:79] op_sel_hi:[0,1,1]
	v_pk_fma_f32 v[88:89], v[4:5], v[52:53], v[88:89]
	v_add_f32_dpp v90, v90, v90 quad_perm:[1,0,3,2] row_mask:0xf bank_mask:0xf bound_ctrl:1
	v_pk_fma_f32 v[84:85], v[76:77], v[70:71], v[80:81] op_sel_hi:[0,1,1]
	ds_read_b128 v[60:63], v110 offset:6400
	v_add_f32_dpp v90, v90, v90 quad_perm:[2,3,0,1] row_mask:0xf bank_mask:0xf bound_ctrl:1
	ds_read_b128 v[56:59], v110 offset:2304
	v_add_f32_e32 v100, v88, v89
	v_add_f32_dpp v90, v90, v90 row_half_mirror row_mask:0xf bank_mask:0xf bound_ctrl:1
	ds_read_b128 v[50:53], v110 offset:18432
	ds_read_b128 v[68:71], v110 offset:14592
	v_add_f32_dpp v92, v90, v90 row_mirror row_mask:0xf bank_mask:0xf bound_ctrl:1
	ds_read_b32 v76, v111 offset:22784
	v_pk_fma_f32 v[2:3], v[92:93], v[64:65], v[82:83] op_sel_hi:[0,1,1] neg_lo:[1,0,0] neg_hi:[1,0,0]
	v_pk_fma_f32 v[4:5], v[92:93], v[66:67], v[84:85] op_sel_hi:[0,1,1] neg_lo:[1,0,0] neg_hi:[1,0,0]
	ds_read_b128 v[64:67], v110 offset:10496
	s_waitcnt lgkmcnt(6)
	v_pk_mul_f32 v[86:87], v[2:3], v[38:39]
	v_pk_mul_f32 v[78:79], v[2:3], v[34:35]
	v_pk_fma_f32 v[86:87], v[4:5], v[40:41], v[86:87]
	v_pk_mul_f32 v[80:81], v[4:5], v[36:37]
	v_pk_mul_f32 v[88:89], v[2:3], v[72:73]
	v_add_f32_e32 v90, v86, v87
	v_pk_fma_f32 v[82:83], v[54:55], v[46:47], v[78:79] op_sel_hi:[0,1,1]
	v_pk_fma_f32 v[88:89], v[4:5], v[74:75], v[88:89]
	v_add_f32_dpp v90, v90, v90 quad_perm:[1,0,3,2] row_mask:0xf bank_mask:0xf bound_ctrl:1
	v_pk_fma_f32 v[84:85], v[54:55], v[48:49], v[80:81] op_sel_hi:[0,1,1]
	ds_read_b128 v[38:41], v110 offset:6656
	v_add_f32_dpp v90, v90, v90 quad_perm:[2,3,0,1] row_mask:0xf bank_mask:0xf bound_ctrl:1
	ds_read_b128 v[34:37], v110 offset:2560
	v_add_f32_e32 v101, v88, v89
	v_add_f32_dpp v90, v90, v90 row_half_mirror row_mask:0xf bank_mask:0xf bound_ctrl:1
	ds_read_b128 v[72:75], v110 offset:18688
	ds_read_b128 v[46:49], v110 offset:14848
	v_add_f32_dpp v92, v90, v90 row_mirror row_mask:0xf bank_mask:0xf bound_ctrl:1
	ds_read_b32 v54, v111 offset:23040
	v_pk_fma_f32 v[2:3], v[92:93], v[42:43], v[82:83] op_sel_hi:[0,1,1] neg_lo:[1,0,0] neg_hi:[1,0,0]
	v_pk_fma_f32 v[4:5], v[92:93], v[44:45], v[84:85] op_sel_hi:[0,1,1] neg_lo:[1,0,0] neg_hi:[1,0,0]
	ds_read_b128 v[42:45], v110 offset:10752
	s_waitcnt lgkmcnt(6)
	v_pk_mul_f32 v[86:87], v[2:3], v[60:61]
	v_pk_mul_f32 v[78:79], v[2:3], v[56:57]
	v_pk_fma_f32 v[86:87], v[4:5], v[62:63], v[86:87]
	v_pk_mul_f32 v[80:81], v[4:5], v[58:59]
	v_pk_mul_f32 v[88:89], v[2:3], v[50:51]
	v_add_f32_e32 v90, v86, v87
	v_pk_fma_f32 v[82:83], v[76:77], v[68:69], v[78:79] op_sel_hi:[0,1,1]
	v_pk_fma_f32 v[88:89], v[4:5], v[52:53], v[88:89]
	v_add_f32_dpp v90, v90, v90 quad_perm:[1,0,3,2] row_mask:0xf bank_mask:0xf bound_ctrl:1
	v_pk_fma_f32 v[84:85], v[76:77], v[70:71], v[80:81] op_sel_hi:[0,1,1]
	ds_read_b128 v[60:63], v110 offset:6912
	v_add_f32_dpp v90, v90, v90 quad_perm:[2,3,0,1] row_mask:0xf bank_mask:0xf bound_ctrl:1
	ds_read_b128 v[56:59], v110 offset:2816
	v_add_f32_e32 v102, v88, v89
	v_add_f32_dpp v90, v90, v90 row_half_mirror row_mask:0xf bank_mask:0xf bound_ctrl:1
	ds_read_b128 v[50:53], v110 offset:18944
	ds_read_b128 v[68:71], v110 offset:15104
	v_add_f32_dpp v92, v90, v90 row_mirror row_mask:0xf bank_mask:0xf bound_ctrl:1
	ds_read_b32 v76, v111 offset:23296
	v_pk_fma_f32 v[2:3], v[92:93], v[64:65], v[82:83] op_sel_hi:[0,1,1] neg_lo:[1,0,0] neg_hi:[1,0,0]
	v_pk_fma_f32 v[4:5], v[92:93], v[66:67], v[84:85] op_sel_hi:[0,1,1] neg_lo:[1,0,0] neg_hi:[1,0,0]
	ds_read_b128 v[64:67], v110 offset:11008
	s_waitcnt lgkmcnt(6)
	v_pk_mul_f32 v[86:87], v[2:3], v[38:39]
	v_pk_mul_f32 v[78:79], v[2:3], v[34:35]
	v_pk_fma_f32 v[86:87], v[4:5], v[40:41], v[86:87]
	v_pk_mul_f32 v[80:81], v[4:5], v[36:37]
	v_pk_mul_f32 v[88:89], v[2:3], v[72:73]
	v_add_f32_e32 v90, v86, v87
	v_pk_fma_f32 v[82:83], v[54:55], v[46:47], v[78:79] op_sel_hi:[0,1,1]
	v_pk_fma_f32 v[88:89], v[4:5], v[74:75], v[88:89]
	v_add_f32_dpp v90, v90, v90 quad_perm:[1,0,3,2] row_mask:0xf bank_mask:0xf bound_ctrl:1
	v_pk_fma_f32 v[84:85], v[54:55], v[48:49], v[80:81] op_sel_hi:[0,1,1]
	ds_read_b128 v[38:41], v110 offset:7168
	v_add_f32_dpp v90, v90, v90 quad_perm:[2,3,0,1] row_mask:0xf bank_mask:0xf bound_ctrl:1
	ds_read_b128 v[34:37], v110 offset:3072
	v_add_f32_e32 v103, v88, v89
	v_add_f32_dpp v90, v90, v90 row_half_mirror row_mask:0xf bank_mask:0xf bound_ctrl:1
	ds_read_b128 v[72:75], v110 offset:19200
	ds_read_b128 v[46:49], v110 offset:15360
	v_add_f32_dpp v92, v90, v90 row_mirror row_mask:0xf bank_mask:0xf bound_ctrl:1
	ds_read_b32 v54, v111 offset:23552
	v_pk_fma_f32 v[2:3], v[92:93], v[42:43], v[82:83] op_sel_hi:[0,1,1] neg_lo:[1,0,0] neg_hi:[1,0,0]
	v_pk_fma_f32 v[4:5], v[92:93], v[44:45], v[84:85] op_sel_hi:[0,1,1] neg_lo:[1,0,0] neg_hi:[1,0,0]
	ds_read_b128 v[42:45], v110 offset:11264
	s_waitcnt lgkmcnt(6)
	v_pk_mul_f32 v[86:87], v[2:3], v[60:61]
	v_pk_mul_f32 v[78:79], v[2:3], v[56:57]
	v_pk_fma_f32 v[86:87], v[4:5], v[62:63], v[86:87]
	v_pk_mul_f32 v[80:81], v[4:5], v[58:59]
	v_pk_mul_f32 v[88:89], v[2:3], v[50:51]
	v_add_f32_e32 v90, v86, v87
	v_pk_fma_f32 v[82:83], v[76:77], v[68:69], v[78:79] op_sel_hi:[0,1,1]
	v_pk_fma_f32 v[88:89], v[4:5], v[52:53], v[88:89]
	v_add_f32_dpp v90, v90, v90 quad_perm:[1,0,3,2] row_mask:0xf bank_mask:0xf bound_ctrl:1
	v_pk_fma_f32 v[84:85], v[76:77], v[70:71], v[80:81] op_sel_hi:[0,1,1]
	ds_read_b128 v[60:63], v110 offset:7424
	v_add_f32_dpp v90, v90, v90 quad_perm:[2,3,0,1] row_mask:0xf bank_mask:0xf bound_ctrl:1
	ds_read_b128 v[56:59], v110 offset:3328
	v_add_f32_e32 v104, v88, v89
	v_add_f32_dpp v90, v90, v90 row_half_mirror row_mask:0xf bank_mask:0xf bound_ctrl:1
	ds_read_b128 v[50:53], v110 offset:19456
	ds_read_b128 v[68:71], v110 offset:15616
	v_add_f32_dpp v92, v90, v90 row_mirror row_mask:0xf bank_mask:0xf bound_ctrl:1
	ds_read_b32 v76, v111 offset:23808
	v_pk_fma_f32 v[2:3], v[92:93], v[64:65], v[82:83] op_sel_hi:[0,1,1] neg_lo:[1,0,0] neg_hi:[1,0,0]
	v_pk_fma_f32 v[4:5], v[92:93], v[66:67], v[84:85] op_sel_hi:[0,1,1] neg_lo:[1,0,0] neg_hi:[1,0,0]
	ds_read_b128 v[64:67], v110 offset:11520
	s_waitcnt lgkmcnt(6)
	v_pk_mul_f32 v[86:87], v[2:3], v[38:39]
	v_pk_mul_f32 v[78:79], v[2:3], v[34:35]
	v_pk_fma_f32 v[86:87], v[4:5], v[40:41], v[86:87]
	v_pk_mul_f32 v[80:81], v[4:5], v[36:37]
	v_pk_mul_f32 v[88:89], v[2:3], v[72:73]
	v_add_f32_e32 v90, v86, v87
	v_pk_fma_f32 v[82:83], v[54:55], v[46:47], v[78:79] op_sel_hi:[0,1,1]
	v_pk_fma_f32 v[88:89], v[4:5], v[74:75], v[88:89]
	v_add_f32_dpp v90, v90, v90 quad_perm:[1,0,3,2] row_mask:0xf bank_mask:0xf bound_ctrl:1
	v_pk_fma_f32 v[84:85], v[54:55], v[48:49], v[80:81] op_sel_hi:[0,1,1]
	ds_read_b128 v[38:41], v110 offset:7680
	v_add_f32_dpp v90, v90, v90 quad_perm:[2,3,0,1] row_mask:0xf bank_mask:0xf bound_ctrl:1
	ds_read_b128 v[34:37], v110 offset:3584
	v_add_f32_e32 v105, v88, v89
	v_add_f32_dpp v90, v90, v90 row_half_mirror row_mask:0xf bank_mask:0xf bound_ctrl:1
	ds_read_b128 v[72:75], v110 offset:19712
	ds_read_b128 v[46:49], v110 offset:15872
	v_add_f32_dpp v92, v90, v90 row_mirror row_mask:0xf bank_mask:0xf bound_ctrl:1
	ds_read_b32 v54, v111 offset:24064
	v_pk_fma_f32 v[2:3], v[92:93], v[42:43], v[82:83] op_sel_hi:[0,1,1] neg_lo:[1,0,0] neg_hi:[1,0,0]
	v_pk_fma_f32 v[4:5], v[92:93], v[44:45], v[84:85] op_sel_hi:[0,1,1] neg_lo:[1,0,0] neg_hi:[1,0,0]
	ds_read_b128 v[42:45], v110 offset:11776
	s_waitcnt lgkmcnt(6)
	v_pk_mul_f32 v[86:87], v[2:3], v[60:61]
	v_pk_mul_f32 v[78:79], v[2:3], v[56:57]
	v_pk_fma_f32 v[86:87], v[4:5], v[62:63], v[86:87]
	v_pk_mul_f32 v[80:81], v[4:5], v[58:59]
	v_pk_mul_f32 v[88:89], v[2:3], v[50:51]
	v_add_f32_e32 v90, v86, v87
	v_pk_fma_f32 v[82:83], v[76:77], v[68:69], v[78:79] op_sel_hi:[0,1,1]
	v_pk_fma_f32 v[88:89], v[4:5], v[52:53], v[88:89]
	v_add_f32_dpp v90, v90, v90 quad_perm:[1,0,3,2] row_mask:0xf bank_mask:0xf bound_ctrl:1
	v_pk_fma_f32 v[84:85], v[76:77], v[70:71], v[80:81] op_sel_hi:[0,1,1]
	ds_read_b128 v[60:63], v110 offset:7936
	v_add_f32_dpp v90, v90, v90 quad_perm:[2,3,0,1] row_mask:0xf bank_mask:0xf bound_ctrl:1
	ds_read_b128 v[56:59], v110 offset:3840
	v_add_f32_e32 v106, v88, v89
	v_add_f32_dpp v90, v90, v90 row_half_mirror row_mask:0xf bank_mask:0xf bound_ctrl:1
	ds_read_b128 v[50:53], v110 offset:19968
	ds_read_b128 v[68:71], v110 offset:16128
	v_add_f32_dpp v92, v90, v90 row_mirror row_mask:0xf bank_mask:0xf bound_ctrl:1
	ds_read_b32 v76, v111 offset:24320
	s_cmpk_eq_i32 s33, 0x10f
	s_cbranch_scc1 .Lscan_tail_last
	v_pk_fma_f32 v[2:3], v[92:93], v[64:65], v[82:83] op_sel_hi:[0,1,1] neg_lo:[1,0,0] neg_hi:[1,0,0]
	v_pk_fma_f32 v[4:5], v[92:93], v[66:67], v[84:85] op_sel_hi:[0,1,1] neg_lo:[1,0,0] neg_hi:[1,0,0]
	ds_read_b128 v[64:67], v110 offset:12032
	s_waitcnt lgkmcnt(6)
	v_pk_mul_f32 v[86:87], v[2:3], v[38:39]
	v_pk_mul_f32 v[78:79], v[2:3], v[34:35]
	v_pk_fma_f32 v[86:87], v[4:5], v[40:41], v[86:87]
	v_pk_mul_f32 v[80:81], v[4:5], v[36:37]
	v_pk_mul_f32 v[88:89], v[2:3], v[72:73]
	v_add_f32_e32 v90, v86, v87
	v_pk_fma_f32 v[82:83], v[54:55], v[46:47], v[78:79] op_sel_hi:[0,1,1]
	v_pk_fma_f32 v[88:89], v[4:5], v[74:75], v[88:89]
	v_add_f32_dpp v90, v90, v90 quad_perm:[1,0,3,2] row_mask:0xf bank_mask:0xf bound_ctrl:1
	v_pk_fma_f32 v[84:85], v[54:55], v[48:49], v[80:81] op_sel_hi:[0,1,1]
	s_waitcnt vmcnt(6)
	v_add_f32_dpp v90, v90, v90 quad_perm:[2,3,0,1] row_mask:0xf bank_mask:0xf bound_ctrl:1
	v_pk_add_f32 v[122:123], v[150:151], -1.0 op_sel_hi:[1,0]
	v_add_f32_e32 v107, v88, v89
	v_add_f32_dpp v90, v90, v90 row_half_mirror row_mask:0xf bank_mask:0xf bound_ctrl:1
	ds_read_b128 v[72:75], v110 offset:20224
	v_pk_add_f32 v[124:125], v[152:153], -1.0 op_sel_hi:[1,0]
	v_add_f32_dpp v92, v90, v90 row_mirror row_mask:0xf bank_mask:0xf bound_ctrl:1
	v_pk_mul_f32 v[118:119], v[154:155], v[150:151]
	v_pk_fma_f32 v[2:3], v[92:93], v[42:43], v[82:83] op_sel_hi:[0,1,1] neg_lo:[1,0,0] neg_hi:[1,0,0]
	v_pk_fma_f32 v[4:5], v[92:93], v[44:45], v[84:85] op_sel_hi:[0,1,1] neg_lo:[1,0,0] neg_hi:[1,0,0]
	v_pk_fma_f32 v[122:123], v[6:7], v[122:123], 1.0 op_sel_hi:[1,1,0]
	s_waitcnt lgkmcnt(1)
	v_pk_mul_f32 v[86:87], v[2:3], v[60:61]
	v_pk_mul_f32 v[78:79], v[2:3], v[56:57]
	v_pk_fma_f32 v[86:87], v[4:5], v[62:63], v[86:87]
	v_pk_mul_f32 v[80:81], v[4:5], v[58:59]
	v_pk_mul_f32 v[88:89], v[2:3], v[50:51]
	v_add_f32_e32 v90, v86, v87
	v_pk_fma_f32 v[82:83], v[76:77], v[68:69], v[78:79] op_sel_hi:[0,1,1]
	v_pk_fma_f32 v[88:89], v[4:5], v[52:53], v[88:89]
	v_add_f32_dpp v90, v90, v90 quad_perm:[1,0,3,2] row_mask:0xf bank_mask:0xf bound_ctrl:1
	v_pk_fma_f32 v[84:85], v[76:77], v[70:71], v[80:81] op_sel_hi:[0,1,1]
	v_pk_fma_f32 v[124:125], v[8:9], v[124:125], 1.0 op_sel_hi:[1,1,0]
	v_add_f32_dpp v90, v90, v90 quad_perm:[2,3,0,1] row_mask:0xf bank_mask:0xf bound_ctrl:1
	v_pk_mul_f32 v[120:121], v[156:157], v[152:153]
	v_add_f32_e32 v108, v88, v89
	v_add_f32_dpp v90, v90, v90 row_half_mirror row_mask:0xf bank_mask:0xf bound_ctrl:1
	v_pk_mul_f32 v[122:123], v[138:139], v[122:123]
	v_pk_mul_f32 v[124:125], v[140:141], v[124:125]
	v_add_f32_dpp v92, v90, v90 row_mirror row_mask:0xf bank_mask:0xf bound_ctrl:1
	ds_write_b128 v112, v[146:149] offset:0
	ds_write_b128 v112, v[154:157] offset:4096
	v_pk_fma_f32 v[2:3], v[92:93], v[64:65], v[82:83] op_sel_hi:[0,1,1] neg_lo:[1,0,0] neg_hi:[1,0,0]
	v_pk_fma_f32 v[4:5], v[92:93], v[66:67], v[84:85] op_sel_hi:[0,1,1] neg_lo:[1,0,0] neg_hi:[1,0,0]
	ds_write_b128 v112, v[134:137] offset:16384
	s_waitcnt lgkmcnt(3)
	v_pk_mul_f32 v[88:89], v[2:3], v[72:73]
	ds_write_b128 v112, v[142:145] offset:20480
	v_pk_fma_f32 v[88:89], v[4:5], v[74:75], v[88:89]
	ds_write_b128 v112, v[118:121] offset:8192
	v_add_f32_e32 v109, v88, v89
	ds_write_b128 v112, v[122:125] offset:12288
	s_waitcnt lgkmcnt(0)
	v_xor_b32_e32 v110, 0x6000, v110
	v_xor_b32_e32 v111, 0x6000, v111
	v_xor_b32_e32 v112, 0x6000, v112
	s_add_i32 s33, s33, 1
	s_barrier
	ds_read_b128 v[38:41], v110 offset:4096
	ds_read_b128 v[34:37], v110 offset:0
	ds_read_b128 v[46:49], v110 offset:12288
	ds_read_b32 v54, v111 offset:20480
	ds_read_b128 v[42:45], v110 offset:8192
	ds_read_b128 v[50:53], v110 offset:16384
	ds_read_b128 v[60:63], v110 offset:4352
	ds_read_b128 v[56:59], v110 offset:256
	ds_read_b128 v[68:71], v110 offset:12544
	ds_read_b32 v76, v111 offset:20736
	ds_read_b128 v[64:67], v110 offset:8448
	ds_read_b128 v[72:75], v110 offset:16640
	s_cmpk_ge_i32 s33, 0x10e
	s_cbranch_scc1 .Lscan_skipload_b
	v_mul_u32_u24_e32 v0, 0xf00, v113
	v_lshl_add_u32 v125, v113, 10, v115
	v_add_u32_e32 v0, v0, v115
	v_add_u32_e32 v113, s34, v113
	global_load_dwordx4 v[146:149], v125, s[46:47]
	global_load_dwordx4 v[150:153], v125, s[48:49]
	global_load_dwordx4 v[154:157], v125, s[22:23]
	global_load_dwordx4 v[138:141], v0, s[12:13] offset:1024
	global_load_dwordx4 v[134:137], v0, s[12:13]
	global_load_dwordx4 v[142:145], v0, s[12:13] offset:2048
	s_cmp_eq_u32 s33, 13
	s_cbranch_scc0 .Lscan_nogload_b
	v_mov_b32_e32 v113, v117
	s_branch .Lscan_nogload_b
.Lscan_skipload_b:
	s_waitcnt vmcnt(0)
.Lscan_nogload_b:
	s_cmp_eq_u32 s33, 0
	s_cbranch_scc1 .Lscan_nored_b
	v_cndmask_b32_e64 v118, v102, v94, s[38:39]
	v_cndmask_b32_e64 v119, v103, v95, s[38:39]
	v_cndmask_b32_e64 v120, v104, v96, s[38:39]
	v_cndmask_b32_e64 v121, v105, v97, s[38:39]
	v_cndmask_b32_e64 v122, v106, v98, s[38:39]
	v_cndmask_b32_e64 v123, v107, v99, s[38:39]
	v_cndmask_b32_e64 v124, v108, v100, s[38:39]
	v_cndmask_b32_e64 v125, v109, v101, s[38:39]
	v_cndmask_b32_e64 v94, v94, v102, s[38:39]
	v_cndmask_b32_e64 v95, v95, v103, s[38:39]
	v_cndmask_b32_e64 v96, v96, v104, s[38:39]
	v_cndmask_b32_e64 v97, v97, v105, s[38:39]
	v_cndmask_b32_e64 v98, v98, v106, s[38:39]
	v_cndmask_b32_e64 v99, v99, v107, s[38:39]
	v_cndmask_b32_e64 v100, v100, v108, s[38:39]
	v_cndmask_b32_e64 v101, v101, v109, s[38:39]
	v_add_f32_dpp v94, v118, v94 row_ror:8 row_mask:0xf bank_mask:0xf bound_ctrl:1
	v_add_f32_dpp v95, v119, v95 row_ror:8 row_mask:0xf bank_mask:0xf bound_ctrl:1
	v_add_f32_dpp v96, v120, v96 row_ror:8 row_mask:0xf bank_mask:0xf bound_ctrl:1
	v_add_f32_dpp v97, v121, v97 row_ror:8 row_mask:0xf bank_mask:0xf bound_ctrl:1
	v_add_f32_dpp v98, v122, v98 row_ror:8 row_mask:0xf bank_mask:0xf bound_ctrl:1
	v_add_f32_dpp v99, v123, v99 row_ror:8 row_mask:0xf bank_mask:0xf bound_ctrl:1
	v_add_f32_dpp v100, v124, v100 row_ror:8 row_mask:0xf bank_mask:0xf bound_ctrl:1
	v_add_f32_dpp v101, v125, v101 row_ror:8 row_mask:0xf bank_mask:0xf bound_ctrl:1
	v_cndmask_b32_e64 v118, v98, v94, s[40:41]
	v_cndmask_b32_e64 v119, v99, v95, s[40:41]
	v_cndmask_b32_e64 v120, v100, v96, s[40:41]
	v_cndmask_b32_e64 v121, v101, v97, s[40:41]
	v_cndmask_b32_e64 v94, v94, v98, s[40:41]
	v_cndmask_b32_e64 v95, v95, v99, s[40:41]
	v_cndmask_b32_e64 v96, v96, v100, s[40:41]
	v_cndmask_b32_e64 v97, v97, v101, s[40:41]
	v_add_f32_dpp v94, v118, v94 row_half_mirror row_mask:0xf bank_mask:0xf bound_ctrl:1
	v_add_f32_dpp v95, v119, v95 row_half_mirror row_mask:0xf bank_mask:0xf bound_ctrl:1
	v_add_f32_dpp v96, v120, v96 row_half_mirror row_mask:0xf bank_mask:0xf bound_ctrl:1
	v_add_f32_dpp v97, v121, v97 row_half_mirror row_mask:0xf bank_mask:0xf bound_ctrl:1
	v_cndmask_b32_e64 v118, v96, v94, s[42:43]
	v_cndmask_b32_e64 v119, v97, v95, s[42:43]
	v_cndmask_b32_e64 v94, v94, v96, s[42:43]
	v_cndmask_b32_e64 v95, v95, v97, s[42:43]
	s_nop 0
	v_add_f32_dpp v94, v118, v94 quad_perm:[1,0,3,2] row_mask:0xf bank_mask:0xf bound_ctrl:1
	v_add_f32_dpp v95, v119, v95 quad_perm:[1,0,3,2] row_mask:0xf bank_mask:0xf bound_ctrl:1
	s_nop 0
	v_cndmask_b32_e64 v118, v95, v94, s[44:45]
	v_cndmask_b32_e64 v94, v94, v95, s[44:45]
	s_nop 1
	v_add_f32_dpp v94, v118, v94 quad_perm:[2,3,0,1] row_mask:0xf bank_mask:0xf bound_ctrl:1
	v_lshl_add_u32 v0, v114, 10, v116
	v_add_u32_e32 v114, s34, v114
	global_store_dword v0, v94, s[50:51]
	s_cmp_eq_u32 s33, 16
	s_cbranch_scc0 .Lscan_nored_b
	v_mov_b32_e32 v114, v126
.Lscan_nored_b:
	s_waitcnt lgkmcnt(1)
	v_pk_mul_f32 v[86:87], v[2:3], v[38:39]
	v_pk_mul_f32 v[78:79], v[2:3], v[34:35]
	v_pk_fma_f32 v[86:87], v[4:5], v[40:41], v[86:87]
	v_pk_mul_f32 v[80:81], v[4:5], v[36:37]
	ds_read_b128 v[38:41], v110 offset:4608
	v_add_f32_e32 v90, v86, v87
	v_pk_fma_f32 v[82:83], v[54:55], v[46:47], v[78:79] op_sel_hi:[0,1,1]
	ds_read_b128 v[34:37], v110 offset:512
	v_add_f32_dpp v90, v90, v90 quad_perm:[1,0,3,2] row_mask:0xf bank_mask:0xf bound_ctrl:1
	v_pk_fma_f32 v[84:85], v[54:55], v[48:49], v[80:81] op_sel_hi:[0,1,1]
	ds_read_b128 v[46:49], v110 offset:12800
	v_add_f32_dpp v90, v90, v90 quad_perm:[2,3,0,1] row_mask:0xf bank_mask:0xf bound_ctrl:1
	ds_read_b32 v54, v111 offset:20992
	s_nop 0
	v_add_f32_dpp v90, v90, v90 row_half_mirror row_mask:0xf bank_mask:0xf bound_ctrl:1
	s_nop 0
	s_nop 0
	v_add_f32_dpp v92, v90, v90 row_mirror row_mask:0xf bank_mask:0xf bound_ctrl:1
	v_pk_fma_f32 v[2:3], v[92:93], v[42:43], v[82:83] op_sel_hi:[0,1,1] neg_lo:[1,0,0] neg_hi:[1,0,0]
	v_pk_fma_f32 v[4:5], v[92:93], v[44:45], v[84:85] op_sel_hi:[0,1,1] neg_lo:[1,0,0] neg_hi:[1,0,0]
	ds_read_b128 v[42:45], v110 offset:8704
	v_pk_mul_f32 v[86:87], v[2:3], v[60:61]
	v_pk_mul_f32 v[78:79], v[2:3], v[56:57]
	v_pk_fma_f32 v[86:87], v[4:5], v[62:63], v[86:87]
	v_pk_mul_f32 v[80:81], v[4:5], v[58:59]
	v_pk_mul_f32 v[88:89], v[2:3], v[50:51]
	v_add_f32_e32 v90, v86, v87
	v_pk_fma_f32 v[82:83], v[76:77], v[68:69], v[78:79] op_sel_hi:[0,1,1]
	v_pk_fma_f32 v[88:89], v[4:5], v[52:53], v[88:89]
	v_add_f32_dpp v90, v90, v90 quad_perm:[1,0,3,2] row_mask:0xf bank_mask:0xf bound_ctrl:1
	v_pk_fma_f32 v[84:85], v[76:77], v[70:71], v[80:81] op_sel_hi:[0,1,1]
	ds_read_b128 v[60:63], v110 offset:4864
	v_add_f32_dpp v90, v90, v90 quad_perm:[2,3,0,1] row_mask:0xf bank_mask:0xf bound_ctrl:1
	ds_read_b128 v[56:59], v110 offset:768
	v_add_f32_e32 v94, v88, v89
	v_add_f32_dpp v90, v90, v90 row_half_mirror row_mask:0xf bank_mask:0xf bound_ctrl:1
	ds_read_b128 v[50:53], v110 offset:16896
	ds_read_b128 v[68:71], v110 offset:13056
	v_add_f32_dpp v92, v90, v90 row_mirror row_mask:0xf bank_mask:0xf bound_ctrl:1
	ds_read_b32 v76, v111 offset:21248
	v_pk_fma_f32 v[2:3], v[92:93], v[64:65], v[82:83] op_sel_hi:[0,1,1] neg_lo:[1,0,0] neg_hi:[1,0,0]
	v_pk_fma_f32 v[4:5], v[92:93], v[66:67], v[84:85] op_sel_hi:[0,1,1] neg_lo:[1,0,0] neg_hi:[1,0,0]
	ds_read_b128 v[64:67], v110 offset:8960
	s_waitcnt lgkmcnt(6)
	v_pk_mul_f32 v[86:87], v[2:3], v[38:39]
	v_pk_mul_f32 v[78:79], v[2:3], v[34:35]
	v_pk_fma_f32 v[86:87], v[4:5], v[40:41], v[86:87]
	v_pk_mul_f32 v[80:81], v[4:5], v[36:37]
	v_pk_mul_f32 v[88:89], v[2:3], v[72:73]
	v_add_f32_e32 v90, v86, v87
	v_pk_fma_f32 v[82:83], v[54:55], v[46:47], v[78:79] op_sel_hi:[0,1,1]
	v_pk_fma_f32 v[88:89], v[4:5], v[74:75], v[88:89]
	v_add_f32_dpp v90, v90, v90 quad_perm:[1,0,3,2] row_mask:0xf bank_mask:0xf bound_ctrl:1
	v_pk_fma_f32 v[84:85], v[54:55], v[48:49], v[80:81] op_sel_hi:[0,1,1]
	ds_read_b128 v[38:41], v110 offset:5120
	v_add_f32_dpp v90, v90, v90 quad_perm:[2,3,0,1] row_mask:0xf bank_mask:0xf bound_ctrl:1
	ds_read_b128 v[34:37], v110 offset:1024
	v_add_f32_e32 v95, v88, v89
	v_add_f32_dpp v90, v90, v90 row_half_mirror row_mask:0xf bank_mask:0xf bound_ctrl:1
	ds_read_b128 v[72:75], v110 offset:17152
	ds_read_b128 v[46:49], v110 offset:13312
	v_add_f32_dpp v92, v90, v90 row_mirror row_mask:0xf bank_mask:0xf bound_ctrl:1
	ds_read_b32 v54, v111 offset:21504
	v_pk_fma_f32 v[2:3], v[92:93], v[42:43], v[82:83] op_sel_hi:[0,1,1] neg_lo:[1,0,0] neg_hi:[1,0,0]
	v_pk_fma_f32 v[4:5], v[92:93], v[44:45], v[84:85] op_sel_hi:[0,1,1] neg_lo:[1,0,0] neg_hi:[1,0,0]
	ds_read_b128 v[42:45], v110 offset:9216
	s_waitcnt lgkmcnt(6)
	v_pk_mul_f32 v[86:87], v[2:3], v[60:61]
	v_pk_mul_f32 v[78:79], v[2:3], v[56:57]
	v_pk_fma_f32 v[86:87], v[4:5], v[62:63], v[86:87]
	v_pk_mul_f32 v[80:81], v[4:5], v[58:59]
	v_pk_mul_f32 v[88:89], v[2:3], v[50:51]
	v_add_f32_e32 v90, v86, v87
	v_pk_fma_f32 v[82:83], v[76:77], v[68:69], v[78:79] op_sel_hi:[0,1,1]
	v_pk_fma_f32 v[88:89], v[4:5], v[52:53], v[88:89]
	v_add_f32_dpp v90, v90, v90 quad_perm:[1,0,3,2] row_mask:0xf bank_mask:0xf bound_ctrl:1
	v_pk_fma_f32 v[84:85], v[76:77], v[70:71], v[80:81] op_sel_hi:[0,1,1]
	ds_read_b128 v[60:63], v110 offset:5376
	v_add_f32_dpp v90, v90, v90 quad_perm:[2,3,0,1] row_mask:0xf bank_mask:0xf bound_ctrl:1
	ds_read_b128 v[56:59], v110 offset:1280
	v_add_f32_e32 v96, v88, v89
	v_add_f32_dpp v90, v90, v90 row_half_mirror row_mask:0xf bank_mask:0xf bound_ctrl:1
	ds_read_b128 v[50:53], v110 offset:17408
	ds_read_b128 v[68:71], v110 offset:13568
	v_add_f32_dpp v92, v90, v90 row_mirror row_mask:0xf bank_mask:0xf bound_ctrl:1
	ds_read_b32 v76, v111 offset:21760
	v_pk_fma_f32 v[2:3], v[92:93], v[64:65], v[82:83] op_sel_hi:[0,1,1] neg_lo:[1,0,0] neg_hi:[1,0,0]
	v_pk_fma_f32 v[4:5], v[92:93], v[66:67], v[84:85] op_sel_hi:[0,1,1] neg_lo:[1,0,0] neg_hi:[1,0,0]
	ds_read_b128 v[64:67], v110 offset:9472
	s_waitcnt lgkmcnt(6)
	v_pk_mul_f32 v[86:87], v[2:3], v[38:39]
	v_pk_mul_f32 v[78:79], v[2:3], v[34:35]
	v_pk_fma_f32 v[86:87], v[4:5], v[40:41], v[86:87]
	v_pk_mul_f32 v[80:81], v[4:5], v[36:37]
	v_pk_mul_f32 v[88:89], v[2:3], v[72:73]
	v_add_f32_e32 v90, v86, v87
	v_pk_fma_f32 v[82:83], v[54:55], v[46:47], v[78:79] op_sel_hi:[0,1,1]
	v_pk_fma_f32 v[88:89], v[4:5], v[74:75], v[88:89]
	v_add_f32_dpp v90, v90, v90 quad_perm:[1,0,3,2] row_mask:0xf bank_mask:0xf bound_ctrl:1
	v_pk_fma_f32 v[84:85], v[54:55], v[48:49], v[80:81] op_sel_hi:[0,1,1]
	ds_read_b128 v[38:41], v110 offset:5632
	v_add_f32_dpp v90, v90, v90 quad_perm:[2,3,0,1] row_mask:0xf bank_mask:0xf bound_ctrl:1
	ds_read_b128 v[34:37], v110 offset:1536
	v_add_f32_e32 v97, v88, v89
	v_add_f32_dpp v90, v90, v90 row_half_mirror row_mask:0xf bank_mask:0xf bound_ctrl:1
	ds_read_b128 v[72:75], v110 offset:17664
	ds_read_b128 v[46:49], v110 offset:13824
	v_add_f32_dpp v92, v90, v90 row_mirror row_mask:0xf bank_mask:0xf bound_ctrl:1
	ds_read_b32 v54, v111 offset:22016
	v_pk_fma_f32 v[2:3], v[92:93], v[42:43], v[82:83] op_sel_hi:[0,1,1] neg_lo:[1,0,0] neg_hi:[1,0,0]
	v_pk_fma_f32 v[4:5], v[92:93], v[44:45], v[84:85] op_sel_hi:[0,1,1] neg_lo:[1,0,0] neg_hi:[1,0,0]
	ds_read_b128 v[42:45], v110 offset:9728
	s_waitcnt lgkmcnt(6)
	v_pk_mul_f32 v[86:87], v[2:3], v[60:61]
	v_pk_mul_f32 v[78:79], v[2:3], v[56:57]
	v_pk_fma_f32 v[86:87], v[4:5], v[62:63], v[86:87]
	v_pk_mul_f32 v[80:81], v[4:5], v[58:59]
	v_pk_mul_f32 v[88:89], v[2:3], v[50:51]
	v_add_f32_e32 v90, v86, v87
	v_pk_fma_f32 v[82:83], v[76:77], v[68:69], v[78:79] op_sel_hi:[0,1,1]
	v_pk_fma_f32 v[88:89], v[4:5], v[52:53], v[88:89]
	v_add_f32_dpp v90, v90, v90 quad_perm:[1,0,3,2] row_mask:0xf bank_mask:0xf bound_ctrl:1
	v_pk_fma_f32 v[84:85], v[76:77], v[70:71], v[80:81] op_sel_hi:[0,1,1]
	ds_read_b128 v[60:63], v110 offset:5888
	v_add_f32_dpp v90, v90, v90 quad_perm:[2,3,0,1] row_mask:0xf bank_mask:0xf bound_ctrl:1
	ds_read_b128 v[56:59], v110 offset:1792
	v_add_f32_e32 v98, v88, v89
	v_add_f32_dpp v90, v90, v90 row_half_mirror row_mask:0xf bank_mask:0xf bound_ctrl:1
	ds_read_b128 v[50:53], v110 offset:17920
	ds_read_b128 v[68:71], v110 offset:14080
	v_add_f32_dpp v92, v90, v90 row_mirror row_mask:0xf bank_mask:0xf bound_ctrl:1
	ds_read_b32 v76, v111 offset:22272
	v_pk_fma_f32 v[2:3], v[92:93], v[64:65], v[82:83] op_sel_hi:[0,1,1] neg_lo:[1,0,0] neg_hi:[1,0,0]
	v_pk_fma_f32 v[4:5], v[92:93], v[66:67], v[84:85] op_sel_hi:[0,1,1] neg_lo:[1,0,0] neg_hi:[1,0,0]
	ds_read_b128 v[64:67], v110 offset:9984
	s_waitcnt lgkmcnt(6)
	v_pk_mul_f32 v[86:87], v[2:3], v[38:39]
	v_pk_mul_f32 v[78:79], v[2:3], v[34:35]
	v_pk_fma_f32 v[86:87], v[4:5], v[40:41], v[86:87]
	v_pk_mul_f32 v[80:81], v[4:5], v[36:37]
	v_pk_mul_f32 v[88:89], v[2:3], v[72:73]
	v_add_f32_e32 v90, v86, v87
	v_pk_fma_f32 v[82:83], v[54:55], v[46:47], v[78:79] op_sel_hi:[0,1,1]
	v_pk_fma_f32 v[88:89], v[4:5], v[74:75], v[88:89]
	v_add_f32_dpp v90, v90, v90 quad_perm:[1,0,3,2] row_mask:0xf bank_mask:0xf bound_ctrl:1
	v_pk_fma_f32 v[84:85], v[54:55], v[48:49], v[80:81] op_sel_hi:[0,1,1]
	ds_read_b128 v[38:41], v110 offset:6144
	v_add_f32_dpp v90, v90, v90 quad_perm:[2,3,0,1] row_mask:0xf bank_mask:0xf bound_ctrl:1
	ds_read_b128 v[34:37], v110 offset:2048
	v_add_f32_e32 v99, v88, v89
	v_add_f32_dpp v90, v90, v90 row_half_mirror row_mask:0xf bank_mask:0xf bound_ctrl:1
	ds_read_b128 v[72:75], v110 offset:18176
	ds_read_b128 v[46:49], v110 offset:14336
	v_add_f32_dpp v92, v90, v90 row_mirror row_mask:0xf bank_mask:0xf bound_ctrl:1
	ds_read_b32 v54, v111 offset:22528
	v_pk_fma_f32 v[2:3], v[92:93], v[42:43], v[82:83] op_sel_hi:[0,1,1] neg_lo:[1,0,0] neg_hi:[1,0,0]
	v_pk_fma_f32 v[4:5], v[92:93], v[44:45], v[84:85] op_sel_hi:[0,1,1] neg_lo:[1,0,0] neg_hi:[1,0,0]
	ds_read_b128 v[42:45], v110 offset:10240
	s_waitcnt lgkmcnt(6)
	v_pk_mul_f32 v[86:87], v[2:3], v[60:61]
	v_pk_mul_f32 v[78:79], v[2:3], v[56:57]
	v_pk_fma_f32 v[86:87], v[4:5], v[62:63], v[86:87]
	v_pk_mul_f32 v[80:81], v[4:5], v[58:59]
	v_pk_mul_f32 v[88:89], v[2:3], v[50:51]
	v_add_f32_e32 v90, v86, v87
	v_pk_fma_f32 v[82:83], v[76:77], v[68:69], v[78:79] op_sel_hi:[0,1,1]
	v_pk_fma_f32 v[88:89], v[4:5], v[52:53], v[88:89]
	v_add_f32_dpp v90, v90, v90 quad_perm:[1,0,3,2] row_mask:0xf bank_mask:0xf bound_ctrl:1
	v_pk_fma_f32 v[84:85], v[76:77], v[70:71], v[80:81] op_sel_hi:[0,1,1]
	ds_read_b128 v[60:63], v110 offset:6400
	v_add_f32_dpp v90, v90, v90 quad_perm:[2,3,0,1] row_mask:0xf bank_mask:0xf bound_ctrl:1
	ds_read_b128 v[56:59], v110 offset:2304
	v_add_f32_e32 v100, v88, v89
	v_add_f32_dpp v90, v90, v90 row_half_mirror row_mask:0xf bank_mask:0xf bound_ctrl:1
	ds_read_b128 v[50:53], v110 offset:18432
	ds_read_b128 v[68:71], v110 offset:14592
	v_add_f32_dpp v92, v90, v90 row_mirror row_mask:0xf bank_mask:0xf bound_ctrl:1
	ds_read_b32 v76, v111 offset:22784
	v_pk_fma_f32 v[2:3], v[92:93], v[64:65], v[82:83] op_sel_hi:[0,1,1] neg_lo:[1,0,0] neg_hi:[1,0,0]
	v_pk_fma_f32 v[4:5], v[92:93], v[66:67], v[84:85] op_sel_hi:[0,1,1] neg_lo:[1,0,0] neg_hi:[1,0,0]
	ds_read_b128 v[64:67], v110 offset:10496
	s_waitcnt lgkmcnt(6)
	v_pk_mul_f32 v[86:87], v[2:3], v[38:39]
	v_pk_mul_f32 v[78:79], v[2:3], v[34:35]
	v_pk_fma_f32 v[86:87], v[4:5], v[40:41], v[86:87]
	v_pk_mul_f32 v[80:81], v[4:5], v[36:37]
	v_pk_mul_f32 v[88:89], v[2:3], v[72:73]
	v_add_f32_e32 v90, v86, v87
	v_pk_fma_f32 v[82:83], v[54:55], v[46:47], v[78:79] op_sel_hi:[0,1,1]
	v_pk_fma_f32 v[88:89], v[4:5], v[74:75], v[88:89]
	v_add_f32_dpp v90, v90, v90 quad_perm:[1,0,3,2] row_mask:0xf bank_mask:0xf bound_ctrl:1
	v_pk_fma_f32 v[84:85], v[54:55], v[48:49], v[80:81] op_sel_hi:[0,1,1]
	ds_read_b128 v[38:41], v110 offset:6656
	v_add_f32_dpp v90, v90, v90 quad_perm:[2,3,0,1] row_mask:0xf bank_mask:0xf bound_ctrl:1
	ds_read_b128 v[34:37], v110 offset:2560
	v_add_f32_e32 v101, v88, v89
	v_add_f32_dpp v90, v90, v90 row_half_mirror row_mask:0xf bank_mask:0xf bound_ctrl:1
	ds_read_b128 v[72:75], v110 offset:18688
	ds_read_b128 v[46:49], v110 offset:14848
	v_add_f32_dpp v92, v90, v90 row_mirror row_mask:0xf bank_mask:0xf bound_ctrl:1
	ds_read_b32 v54, v111 offset:23040
	v_pk_fma_f32 v[2:3], v[92:93], v[42:43], v[82:83] op_sel_hi:[0,1,1] neg_lo:[1,0,0] neg_hi:[1,0,0]
	v_pk_fma_f32 v[4:5], v[92:93], v[44:45], v[84:85] op_sel_hi:[0,1,1] neg_lo:[1,0,0] neg_hi:[1,0,0]
	ds_read_b128 v[42:45], v110 offset:10752
	s_waitcnt lgkmcnt(6)
	v_pk_mul_f32 v[86:87], v[2:3], v[60:61]
	v_pk_mul_f32 v[78:79], v[2:3], v[56:57]
	v_pk_fma_f32 v[86:87], v[4:5], v[62:63], v[86:87]
	v_pk_mul_f32 v[80:81], v[4:5], v[58:59]
	v_pk_mul_f32 v[88:89], v[2:3], v[50:51]
	v_add_f32_e32 v90, v86, v87
	v_pk_fma_f32 v[82:83], v[76:77], v[68:69], v[78:79] op_sel_hi:[0,1,1]
	v_pk_fma_f32 v[88:89], v[4:5], v[52:53], v[88:89]
	v_add_f32_dpp v90, v90, v90 quad_perm:[1,0,3,2] row_mask:0xf bank_mask:0xf bound_ctrl:1
	v_pk_fma_f32 v[84:85], v[76:77], v[70:71], v[80:81] op_sel_hi:[0,1,1]
	ds_read_b128 v[60:63], v110 offset:6912
	v_add_f32_dpp v90, v90, v90 quad_perm:[2,3,0,1] row_mask:0xf bank_mask:0xf bound_ctrl:1
	ds_read_b128 v[56:59], v110 offset:2816
	v_add_f32_e32 v102, v88, v89
	v_add_f32_dpp v90, v90, v90 row_half_mirror row_mask:0xf bank_mask:0xf bound_ctrl:1
	ds_read_b128 v[50:53], v110 offset:18944
	ds_read_b128 v[68:71], v110 offset:15104
	v_add_f32_dpp v92, v90, v90 row_mirror row_mask:0xf bank_mask:0xf bound_ctrl:1
	ds_read_b32 v76, v111 offset:23296
	v_pk_fma_f32 v[2:3], v[92:93], v[64:65], v[82:83] op_sel_hi:[0,1,1] neg_lo:[1,0,0] neg_hi:[1,0,0]
	v_pk_fma_f32 v[4:5], v[92:93], v[66:67], v[84:85] op_sel_hi:[0,1,1] neg_lo:[1,0,0] neg_hi:[1,0,0]
	ds_read_b128 v[64:67], v110 offset:11008
	s_waitcnt lgkmcnt(6)
	v_pk_mul_f32 v[86:87], v[2:3], v[38:39]
	v_pk_mul_f32 v[78:79], v[2:3], v[34:35]
	v_pk_fma_f32 v[86:87], v[4:5], v[40:41], v[86:87]
	v_pk_mul_f32 v[80:81], v[4:5], v[36:37]
	v_pk_mul_f32 v[88:89], v[2:3], v[72:73]
	v_add_f32_e32 v90, v86, v87
	v_pk_fma_f32 v[82:83], v[54:55], v[46:47], v[78:79] op_sel_hi:[0,1,1]
	v_pk_fma_f32 v[88:89], v[4:5], v[74:75], v[88:89]
	v_add_f32_dpp v90, v90, v90 quad_perm:[1,0,3,2] row_mask:0xf bank_mask:0xf bound_ctrl:1
	v_pk_fma_f32 v[84:85], v[54:55], v[48:49], v[80:81] op_sel_hi:[0,1,1]
	ds_read_b128 v[38:41], v110 offset:7168
	v_add_f32_dpp v90, v90, v90 quad_perm:[2,3,0,1] row_mask:0xf bank_mask:0xf bound_ctrl:1
	ds_read_b128 v[34:37], v110 offset:3072
	v_add_f32_e32 v103, v88, v89
	v_add_f32_dpp v90, v90, v90 row_half_mirror row_mask:0xf bank_mask:0xf bound_ctrl:1
	ds_read_b128 v[72:75], v110 offset:19200
	ds_read_b128 v[46:49], v110 offset:15360
	v_add_f32_dpp v92, v90, v90 row_mirror row_mask:0xf bank_mask:0xf bound_ctrl:1
	ds_read_b32 v54, v111 offset:23552
	v_pk_fma_f32 v[2:3], v[92:93], v[42:43], v[82:83] op_sel_hi:[0,1,1] neg_lo:[1,0,0] neg_hi:[1,0,0]
	v_pk_fma_f32 v[4:5], v[92:93], v[44:45], v[84:85] op_sel_hi:[0,1,1] neg_lo:[1,0,0] neg_hi:[1,0,0]
	ds_read_b128 v[42:45], v110 offset:11264
	s_waitcnt lgkmcnt(6)
	v_pk_mul_f32 v[86:87], v[2:3], v[60:61]
	v_pk_mul_f32 v[78:79], v[2:3], v[56:57]
	v_pk_fma_f32 v[86:87], v[4:5], v[62:63], v[86:87]
	v_pk_mul_f32 v[80:81], v[4:5], v[58:59]
	v_pk_mul_f32 v[88:89], v[2:3], v[50:51]
	v_add_f32_e32 v90, v86, v87
	v_pk_fma_f32 v[82:83], v[76:77], v[68:69], v[78:79] op_sel_hi:[0,1,1]
	v_pk_fma_f32 v[88:89], v[4:5], v[52:53], v[88:89]
	v_add_f32_dpp v90, v90, v90 quad_perm:[1,0,3,2] row_mask:0xf bank_mask:0xf bound_ctrl:1
	v_pk_fma_f32 v[84:85], v[76:77], v[70:71], v[80:81] op_sel_hi:[0,1,1]
	ds_read_b128 v[60:63], v110 offset:7424
	v_add_f32_dpp v90, v90, v90 quad_perm:[2,3,0,1] row_mask:0xf bank_mask:0xf bound_ctrl:1
	ds_read_b128 v[56:59], v110 offset:3328
	v_add_f32_e32 v104, v88, v89
	v_add_f32_dpp v90, v90, v90 row_half_mirror row_mask:0xf bank_mask:0xf bound_ctrl:1
	ds_read_b128 v[50:53], v110 offset:19456
	ds_read_b128 v[68:71], v110 offset:15616
	v_add_f32_dpp v92, v90, v90 row_mirror row_mask:0xf bank_mask:0xf bound_ctrl:1
	ds_read_b32 v76, v111 offset:23808
	v_pk_fma_f32 v[2:3], v[92:93], v[64:65], v[82:83] op_sel_hi:[0,1,1] neg_lo:[1,0,0] neg_hi:[1,0,0]
	v_pk_fma_f32 v[4:5], v[92:93], v[66:67], v[84:85] op_sel_hi:[0,1,1] neg_lo:[1,0,0] neg_hi:[1,0,0]
	ds_read_b128 v[64:67], v110 offset:11520
	s_waitcnt lgkmcnt(6)
	v_pk_mul_f32 v[86:87], v[2:3], v[38:39]
	v_pk_mul_f32 v[78:79], v[2:3], v[34:35]
	v_pk_fma_f32 v[86:87], v[4:5], v[40:41], v[86:87]
	v_pk_mul_f32 v[80:81], v[4:5], v[36:37]
	v_pk_mul_f32 v[88:89], v[2:3], v[72:73]
	v_add_f32_e32 v90, v86, v87
	v_pk_fma_f32 v[82:83], v[54:55], v[46:47], v[78:79] op_sel_hi:[0,1,1]
	v_pk_fma_f32 v[88:89], v[4:5], v[74:75], v[88:89]
	v_add_f32_dpp v90, v90, v90 quad_perm:[1,0,3,2] row_mask:0xf bank_mask:0xf bound_ctrl:1
	v_pk_fma_f32 v[84:85], v[54:55], v[48:49], v[80:81] op_sel_hi:[0,1,1]
	ds_read_b128 v[38:41], v110 offset:7680
	v_add_f32_dpp v90, v90, v90 quad_perm:[2,3,0,1] row_mask:0xf bank_mask:0xf bound_ctrl:1
	ds_read_b128 v[34:37], v110 offset:3584
	v_add_f32_e32 v105, v88, v89
	v_add_f32_dpp v90, v90, v90 row_half_mirror row_mask:0xf bank_mask:0xf bound_ctrl:1
	ds_read_b128 v[72:75], v110 offset:19712
	ds_read_b128 v[46:49], v110 offset:15872
	v_add_f32_dpp v92, v90, v90 row_mirror row_mask:0xf bank_mask:0xf bound_ctrl:1
	ds_read_b32 v54, v111 offset:24064
	v_pk_fma_f32 v[2:3], v[92:93], v[42:43], v[82:83] op_sel_hi:[0,1,1] neg_lo:[1,0,0] neg_hi:[1,0,0]
	v_pk_fma_f32 v[4:5], v[92:93], v[44:45], v[84:85] op_sel_hi:[0,1,1] neg_lo:[1,0,0] neg_hi:[1,0,0]
	ds_read_b128 v[42:45], v110 offset:11776
	s_waitcnt lgkmcnt(6)
	v_pk_mul_f32 v[86:87], v[2:3], v[60:61]
	v_pk_mul_f32 v[78:79], v[2:3], v[56:57]
	v_pk_fma_f32 v[86:87], v[4:5], v[62:63], v[86:87]
	v_pk_mul_f32 v[80:81], v[4:5], v[58:59]
	v_pk_mul_f32 v[88:89], v[2:3], v[50:51]
	v_add_f32_e32 v90, v86, v87
	v_pk_fma_f32 v[82:83], v[76:77], v[68:69], v[78:79] op_sel_hi:[0,1,1]
	v_pk_fma_f32 v[88:89], v[4:5], v[52:53], v[88:89]
	v_add_f32_dpp v90, v90, v90 quad_perm:[1,0,3,2] row_mask:0xf bank_mask:0xf bound_ctrl:1
	v_pk_fma_f32 v[84:85], v[76:77], v[70:71], v[80:81] op_sel_hi:[0,1,1]
	ds_read_b128 v[60:63], v110 offset:7936
	v_add_f32_dpp v90, v90, v90 quad_perm:[2,3,0,1] row_mask:0xf bank_mask:0xf bound_ctrl:1
	ds_read_b128 v[56:59], v110 offset:3840
	v_add_f32_e32 v106, v88, v89
	v_add_f32_dpp v90, v90, v90 row_half_mirror row_mask:0xf bank_mask:0xf bound_ctrl:1
	ds_read_b128 v[50:53], v110 offset:19968
	ds_read_b128 v[68:71], v110 offset:16128
	v_add_f32_dpp v92, v90, v90 row_mirror row_mask:0xf bank_mask:0xf bound_ctrl:1
	ds_read_b32 v76, v111 offset:24320
	s_cmpk_eq_i32 s33, 0x10f
	s_cbranch_scc1 .Lscan_tail_last
	v_pk_fma_f32 v[2:3], v[92:93], v[64:65], v[82:83] op_sel_hi:[0,1,1] neg_lo:[1,0,0] neg_hi:[1,0,0]
	v_pk_fma_f32 v[4:5], v[92:93], v[66:67], v[84:85] op_sel_hi:[0,1,1] neg_lo:[1,0,0] neg_hi:[1,0,0]
	ds_read_b128 v[64:67], v110 offset:12032
	s_waitcnt lgkmcnt(6)
	v_pk_mul_f32 v[86:87], v[2:3], v[38:39]
	v_pk_mul_f32 v[78:79], v[2:3], v[34:35]
	v_pk_fma_f32 v[86:87], v[4:5], v[40:41], v[86:87]
	v_pk_mul_f32 v[80:81], v[4:5], v[36:37]
	v_pk_mul_f32 v[88:89], v[2:3], v[72:73]
	v_add_f32_e32 v90, v86, v87
	v_pk_fma_f32 v[82:83], v[54:55], v[46:47], v[78:79] op_sel_hi:[0,1,1]
	v_pk_fma_f32 v[88:89], v[4:5], v[74:75], v[88:89]
	v_add_f32_dpp v90, v90, v90 quad_perm:[1,0,3,2] row_mask:0xf bank_mask:0xf bound_ctrl:1
	v_pk_fma_f32 v[84:85], v[54:55], v[48:49], v[80:81] op_sel_hi:[0,1,1]
	s_waitcnt vmcnt(6)
	v_add_f32_dpp v90, v90, v90 quad_perm:[2,3,0,1] row_mask:0xf bank_mask:0xf bound_ctrl:1
	v_pk_add_f32 v[122:123], v[26:27], -1.0 op_sel_hi:[1,0]
	v_add_f32_e32 v107, v88, v89
	v_add_f32_dpp v90, v90, v90 row_half_mirror row_mask:0xf bank_mask:0xf bound_ctrl:1
	ds_read_b128 v[72:75], v110 offset:20224
	v_pk_add_f32 v[124:125], v[28:29], -1.0 op_sel_hi:[1,0]
	v_add_f32_dpp v92, v90, v90 row_mirror row_mask:0xf bank_mask:0xf bound_ctrl:1
	v_pk_mul_f32 v[118:119], v[30:31], v[26:27]
	v_pk_fma_f32 v[2:3], v[92:93], v[42:43], v[82:83] op_sel_hi:[0,1,1] neg_lo:[1,0,0] neg_hi:[1,0,0]
	v_pk_fma_f32 v[4:5], v[92:93], v[44:45], v[84:85] op_sel_hi:[0,1,1] neg_lo:[1,0,0] neg_hi:[1,0,0]
	v_pk_fma_f32 v[122:123], v[6:7], v[122:123], 1.0 op_sel_hi:[1,1,0]
	s_waitcnt lgkmcnt(1)
	v_pk_mul_f32 v[86:87], v[2:3], v[60:61]
	v_pk_mul_f32 v[78:79], v[2:3], v[56:57]
	v_pk_fma_f32 v[86:87], v[4:5], v[62:63], v[86:87]
	v_pk_mul_f32 v[80:81], v[4:5], v[58:59]
	v_pk_mul_f32 v[88:89], v[2:3], v[50:51]
	v_add_f32_e32 v90, v86, v87
	v_pk_fma_f32 v[82:83], v[76:77], v[68:69], v[78:79] op_sel_hi:[0,1,1]
	v_pk_fma_f32 v[88:89], v[4:5], v[52:53], v[88:89]
	v_add_f32_dpp v90, v90, v90 quad_perm:[1,0,3,2] row_mask:0xf bank_mask:0xf bound_ctrl:1
	v_pk_fma_f32 v[84:85], v[76:77], v[70:71], v[80:81] op_sel_hi:[0,1,1]
	v_pk_fma_f32 v[124:125], v[8:9], v[124:125], 1.0 op_sel_hi:[1,1,0]
	v_add_f32_dpp v90, v90, v90 quad_perm:[2,3,0,1] row_mask:0xf bank_mask:0xf bound_ctrl:1
	v_pk_mul_f32 v[120:121], v[32:33], v[28:29]
	v_add_f32_e32 v108, v88, v89
	v_add_f32_dpp v90, v90, v90 row_half_mirror row_mask:0xf bank_mask:0xf bound_ctrl:1
	v_pk_mul_f32 v[122:123], v[14:15], v[122:123]
	v_pk_mul_f32 v[124:125], v[16:17], v[124:125]
	v_add_f32_dpp v92, v90, v90 row_mirror row_mask:0xf bank_mask:0xf bound_ctrl:1
	ds_write_b128 v112, v[22:25] offset:0
	ds_write_b128 v112, v[30:33] offset:4096
	v_pk_fma_f32 v[2:3], v[92:93], v[64:65], v[82:83] op_sel_hi:[0,1,1] neg_lo:[1,0,0] neg_hi:[1,0,0]
	v_pk_fma_f32 v[4:5], v[92:93], v[66:67], v[84:85] op_sel_hi:[0,1,1] neg_lo:[1,0,0] neg_hi:[1,0,0]
	ds_write_b128 v112, v[10:13] offset:16384
	s_waitcnt lgkmcnt(3)
	v_pk_mul_f32 v[88:89], v[2:3], v[72:73]
	ds_write_b128 v112, v[18:21] offset:20480
	v_pk_fma_f32 v[88:89], v[4:5], v[74:75], v[88:89]
	ds_write_b128 v112, v[118:121] offset:8192
	v_add_f32_e32 v109, v88, v89
	ds_write_b128 v112, v[122:125] offset:12288
	s_waitcnt lgkmcnt(0)
	v_xor_b32_e32 v110, 0x6000, v110
	v_xor_b32_e32 v111, 0x6000, v111
	v_xor_b32_e32 v112, 0x6000, v112
	s_add_i32 s33, s33, 1
	s_barrier
	s_branch .Lscan_chunk
